# attention loop: SGPR-base LDS-DMA addressing (SALU pointer advance), drop no-op canonicalising max/add0
# speedup vs baseline: 1.0233x; 1.0024x over previous
.LBB0_379:
	s_and_b32 s22, s25, 0x3fffffc0
	s_lshl_b32 s22, s22, 2
	v_lshlrev_b32_e32 v0, 10, v201
	v_lshlrev_b32_e32 v2, 4, v200
	s_add_i32 s31, s22, 0
	v_add3_u32 v208, 0, v0, v2
	v_mov_b32_e32 v2, v1
	v_mov_b32_e32 v3, v1
	v_mov_b32_e32 v4, v1
	v_mov_b32_e32 v5, v1
	v_mov_b32_e32 v6, v1
	v_mov_b32_e32 v7, v1
	v_mov_b32_e32 v8, v1
	v_mov_b32_e32 v9, v1
	v_mov_b32_e32 v10, v1
	v_mov_b32_e32 v11, v1
	v_mov_b32_e32 v12, v1
	v_mov_b32_e32 v13, v1
	v_mov_b32_e32 v14, v1
	v_mov_b32_e32 v15, v1
	s_cmp_lg_u32 0, -1
	v_mov_b32_e32 v0, v1
	v_mov_b64_e32 v[16:17], v[14:15]
	s_cselect_b32 s22, 0, 0
	v_mov_b64_e32 v[14:15], v[12:13]
	v_mov_b64_e32 v[12:13], v[10:11]
	v_mov_b64_e32 v[10:11], v[8:9]
	v_mov_b64_e32 v[8:9], v[6:7]
	v_mov_b64_e32 v[6:7], v[4:5]
	v_mov_b64_e32 v[4:5], v[2:3]
	v_mov_b64_e32 v[2:3], v[0:1]
	s_add_i32 s12, s22, s12
	v_lshl_add_u64 v[26:27], v[82:83], 0, s[62:63]
	s_add_i32 s22, s12, 0x4000
	s_mov_b32 s23, m0
	s_mov_b32 m0, s22
	s_nop 0
	global_load_lds_dwordx4 v[26:27], off
	s_mov_b32 m0, s23
	s_waitcnt vmcnt(3) lgkmcnt(0)
	s_barrier
	ds_read_b128 v[66:69], v208
	ds_read_b128 v[70:73], v208 offset:512
	v_pk_mul_f32 v[24:25], v[24:25], s[60:61] op_sel_hi:[1,0]
	v_pk_mul_f32 v[22:23], v[22:23], s[60:61] op_sel_hi:[1,0]
	v_pk_mul_f32 v[20:21], v[20:21], s[60:61] op_sel_hi:[1,0]
	v_pk_mul_f32 v[18:19], v[18:19], s[60:61] op_sel_hi:[1,0]
	v_cvt_pk_bf16_f32 v142, v24, v25
	v_cvt_pk_bf16_f32 v143, v22, v23
	v_cvt_pk_bf16_f32 v144, v20, v21
	v_cvt_pk_bf16_f32 v145, v18, v19
	v_pk_mul_f32 v[44:45], v[44:45], s[60:61] op_sel_hi:[1,0]
	v_pk_mul_f32 v[42:43], v[42:43], s[60:61] op_sel_hi:[1,0]
	s_waitcnt lgkmcnt(1)
	v_mfma_f32_32x32x16_bf16 v[18:33], v[66:69], v[142:145], v[2:17]
	ds_read_b128 v[66:69], v208 offset:2048
	v_cvt_pk_bf16_f32 v136, v44, v45
	v_cvt_pk_bf16_f32 v137, v42, v43
	ds_read_b128 v[42:45], v208 offset:2560
	v_mul_f32_e64 v48, v48, s60
	v_mul_f32_e64 v49, v49, s60
	v_pk_mul_f32 v[46:47], v[46:47], s[60:61] op_sel_hi:[1,0]
	v_cvt_pk_bf16_f32 v134, v48, v49
	s_waitcnt lgkmcnt(2)
	v_mfma_f32_32x32x16_bf16 v[2:17], v[70:73], v[142:145], v[2:17]
	v_cvt_pk_bf16_f32 v135, v46, v47
	v_mov_b32_e32 v63, v53
	v_mov_b32_e32 v61, v55
	v_mov_b32_e32 v59, v57
	ds_read_b128 v[46:49], v208 offset:4096
	v_mov_b32_e32 v65, v51
	v_pk_mul_f32 v[50:51], v[64:65], s[60:61] op_sel_hi:[1,0]
	s_waitcnt lgkmcnt(1)
	v_mfma_f32_32x32x16_bf16 v[2:17], v[42:45], v[134:137], v[2:17]
	v_mul_f32_e64 v42, v62, s60
	v_mul_f32_e64 v43, v63, s60
	v_cvt_pk_bf16_f32 v126, v50, v51
	v_cvt_pk_bf16_f32 v127, v42, v43
	v_mul_f32_e64 v42, v60, s60
	v_mul_f32_e64 v43, v61, s60
	v_pk_mul_f32 v[34:35], v[34:35], s[60:61] op_sel_hi:[1,0]
	v_cvt_pk_bf16_f32 v128, v42, v43
	v_pk_mul_f32 v[42:43], v[58:59], s[60:61] op_sel_hi:[1,0]
	v_mfma_f32_32x32x16_bf16 v[18:33], v[66:69], v[134:137], v[18:33]
	v_cvt_pk_bf16_f32 v129, v42, v43
	ds_read_b128 v[42:45], v208 offset:4608
	v_lshlrev_b32_e32 v0, 1, v86
	v_cvt_pk_bf16_f32 v119, v34, v35
	v_mul_f32_e64 v34, v36, s60
	v_mul_f32_e64 v35, v37, s60
	v_and_b32_e32 v205, 32, v0
	v_pk_mul_f32 v[38:39], v[38:39], s[60:61] op_sel_hi:[1,0]
	s_waitcnt lgkmcnt(1)
	v_mfma_f32_32x32x16_bf16 v[18:33], v[46:49], v[126:129], v[18:33]
	ds_read_b128 v[46:49], v208 offset:6656
	ds_read_b128 v[50:53], v208 offset:6144
	v_cvt_pk_bf16_f32 v120, v34, v35
	v_mul_f32_e64 v34, v40, s60
	v_mul_f32_e64 v35, v41, s60
	v_lshlrev_b32_e32 v0, 4, v86
	v_cvt_pk_bf16_f32 v118, v38, v39
	v_cvt_pk_bf16_f32 v121, v34, v35
	v_and_b32_e32 v0, 0xc0, v0
	s_waitcnt lgkmcnt(2)
	v_mfma_f32_32x32x16_bf16 v[2:17], v[42:45], v[126:129], v[2:17]
	v_lshl_or_b32 v204, v201, 8, v0
	v_add_u32_e32 v0, 0, v205
	v_add3_u32 v209, v0, v202, v204
	s_mov_b64 s[38:39], 0x4000
	s_add_i32 s12, s12, 0x8000
	s_mov_b32 s22, 1
	s_mov_b32 s36, 0
	s_waitcnt lgkmcnt(0)
	v_mfma_f32_32x32x16_bf16 v[18:33], v[50:53], v[118:121], v[18:33]
	s_movk_i32 s37, 0x4000
	s_and_b64 vcc, exec, s[4:5]
	v_cmp_gt_u32_e64 s[4:5], 32, v198
	v_lshl_add_u32 v206, v200, 2, s31
	s_mul_hi_u32 s40, s20, 0x110000
	v_mfma_f32_32x32x16_bf16 v[2:17], v[46:49], v[118:121], v[2:17]
	s_nop 15
	s_nop 7
	s_nop 0
	v_max3_f32 v0, v18, v19, v2
	v_max3_f32 v34, v20, v21, v3
	s_nop 0
	v_max3_f32 v0, v0, v4, v5
	v_max3_f32 v34, v34, v24, v25
	s_nop 0
	v_max3_f32 v0, v0, v22, v23
	v_max3_f32 v34, v34, v8, v9
	s_nop 0
	v_max3_f32 v0, v0, v6, v7
	v_max3_f32 v34, v34, v28, v29
	s_nop 0
	v_max3_f32 v0, v0, v26, v27
	v_max3_f32 v34, v34, v12, v13
	s_nop 0
	v_max3_f32 v0, v0, v10, v11
	v_max3_f32 v34, v34, v32, v33
	s_nop 0
	v_max3_f32 v0, v0, v30, v31
	v_max3_f32 v34, v34, v16, v17
	s_nop 0
	v_max3_f32 v0, v0, v14, v15
	s_nop 0
	v_max_f32_e32 v0, v0, v34
	s_nop 0
	v_mov_b32_e32 v34, v0
	s_nop 1
	v_permlane32_swap_b32_e32 v0, v34
	v_max_f32_e32 v0, v0, v34
	s_nop 0
	v_add_f32_e32 v207, v1, v0
	v_sub_f32_e32 v2, v2, v0
	v_sub_f32_e32 v3, v3, v0
	v_sub_f32_e32 v18, v18, v0
	v_sub_f32_e32 v19, v19, v0
	v_sub_f32_e32 v20, v20, v0
	s_nop 0
	v_xor_b32_e32 v34, 0x80000000, v207
	v_mov_b32_e32 v35, v34
	v_mov_b32_e32 v36, v34
	v_mov_b32_e32 v37, v34
	v_mov_b32_e32 v38, v34
	v_mov_b32_e32 v39, v34
	v_mov_b32_e32 v40, v34
	v_mov_b32_e32 v41, v34
	v_mov_b32_e32 v42, v34
	v_mov_b32_e32 v43, v34
	v_mov_b32_e32 v44, v34
	v_mov_b32_e32 v45, v34
	v_mov_b32_e32 v46, v34
	v_mov_b32_e32 v47, v34
	v_mov_b32_e32 v48, v34
	v_mov_b32_e32 v49, v34
	s_waitcnt vmcnt(0) lgkmcnt(0)
	s_barrier
	v_exp_f32_e32 v50, v2
	v_exp_f32_e32 v51, v3
	v_lshl_add_u64 v[2:3], v[82:83], 0, s[64:65]
	s_mov_b32 s23, m0
	s_mov_b32 m0, s29
	s_nop 0
	global_load_lds_dwordx4 v[2:3], off
	s_mov_b32 m0, s23
	v_lshl_add_u64 v[2:3], v[84:85], 0, s[38:39]
	s_mov_b32 s23, m0
	s_mov_b32 m0, s12
	s_nop 0
	global_load_lds_dwordx4 v[2:3], off
	s_mov_b32 m0, s23
	ds_read_b128 v[174:177], v208 offset:8192
	ds_read_b128 v[170:173], v208 offset:8704
	ds_read_b128 v[166:169], v208 offset:10240
	ds_read_b128 v[162:165], v208 offset:10752
	ds_read_b128 v[158:161], v208 offset:12288
	ds_read_b128 v[154:157], v208 offset:12800
	ds_read_b128 v[150:153], v208 offset:14336
	ds_read_b128 v[146:149], v208 offset:14848
	v_sub_f32_e32 v4, v4, v0
	v_sub_f32_e32 v21, v21, v0
	v_sub_f32_e32 v5, v5, v0
	v_sub_f32_e32 v22, v22, v0
	v_sub_f32_e32 v6, v6, v0
	v_sub_f32_e32 v23, v23, v0
	v_sub_f32_e32 v7, v7, v0
	v_sub_f32_e32 v24, v24, v0
	v_sub_f32_e32 v8, v8, v0
	v_sub_f32_e32 v25, v25, v0
	v_sub_f32_e32 v9, v9, v0
	v_sub_f32_e32 v26, v26, v0
	v_sub_f32_e32 v10, v10, v0
	v_sub_f32_e32 v27, v27, v0
	v_sub_f32_e32 v11, v11, v0
	v_sub_f32_e32 v28, v28, v0
	v_sub_f32_e32 v12, v12, v0
	v_sub_f32_e32 v29, v29, v0
	v_sub_f32_e32 v13, v13, v0
	v_sub_f32_e32 v30, v30, v0
	v_sub_f32_e32 v14, v14, v0
	v_sub_f32_e32 v31, v31, v0
	v_sub_f32_e32 v15, v15, v0
	v_sub_f32_e32 v32, v32, v0
	v_sub_f32_e32 v16, v16, v0
	v_sub_f32_e32 v33, v33, v0
	v_sub_f32_e32 v0, v17, v0
	v_exp_f32_e32 v66, v18
	v_exp_f32_e32 v67, v19
	v_exp_f32_e32 v68, v20
	v_exp_f32_e32 v69, v21
	v_exp_f32_e32 v70, v22
	v_exp_f32_e32 v71, v23
	v_exp_f32_e32 v72, v24
	v_exp_f32_e32 v73, v25
	v_exp_f32_e32 v74, v26
	v_exp_f32_e32 v75, v27
	v_exp_f32_e32 v76, v28
	v_exp_f32_e32 v77, v29
	v_exp_f32_e32 v78, v30
	v_exp_f32_e32 v79, v31
	v_exp_f32_e32 v80, v32
	v_exp_f32_e32 v81, v33
	v_exp_f32_e32 v52, v4
	v_exp_f32_e32 v53, v5
	v_exp_f32_e32 v54, v6
	v_exp_f32_e32 v55, v7
	v_exp_f32_e32 v56, v8
	v_exp_f32_e32 v57, v9
	v_exp_f32_e32 v58, v10
	v_exp_f32_e32 v59, v11
	v_exp_f32_e32 v60, v12
	v_exp_f32_e32 v61, v13
	v_exp_f32_e32 v62, v14
	v_exp_f32_e32 v63, v15
	v_exp_f32_e32 v64, v16
	v_exp_f32_e32 v65, v0
	s_waitcnt vmcnt(2) lgkmcnt(0)
	s_barrier
	v_and_b32_e32 v0, 3, v86
	s_mul_i32 s39, s21, 0x110000
	s_mul_i32 s38, s20, 0x110000
	v_lshlrev_b32_e32 v0, 4, v0
	s_cbranch_vccnz .LBB0_395
	s_lshl_b32 s12, s24, 5
	s_and_b32 s12, s12, 0x80
	s_add_i32 s22, s40, s39
	s_lshl_b64 s[20:21], s[18:19], 1
	s_add_u32 s20, s20, s38
	s_addc_u32 s21, s21, s22
	v_lshl_add_u64 v[2:3], s[20:21], 0, v[0:1]
	s_lshl_b32 s20, s25, 6
	s_and_b32 s20, s20, 0x3000
	v_lshl_or_b32 v4, v192, 8, s20
	s_lshl_b64 s[20:21], s[6:7], 1
	s_add_u32 s20, s46, s20
	s_addc_u32 s21, s47, s21
	v_mov_b32_e32 v5, v1
	s_add_u32 s20, s20, s38
	v_lshl_add_u64 v[2:3], v[2:3], 0, v[4:5]
	v_mov_b32_e32 v183, v1
	s_addc_u32 s21, s21, s22
	v_mov_b32_e32 v194, 0
	s_mov_b32 s41, 6
	v_lshl_add_u64 v[184:185], s[46:47], 0, v[2:3]
	v_lshl_add_u64 v[186:187], s[20:21], 0, v[182:183]
	s_movk_i32 s36, 0x4000
	s_movk_i32 s72, 0x2000
	s_mov_b32 s20, 0
	v_mov_b32_e32 v18, 0
	v_mov_b32_e32 v19, v194
	v_mov_b32_e32 v20, v194
	v_mov_b32_e32 v21, v194
	v_mov_b32_e32 v22, v194
	v_mov_b32_e32 v23, v194
	v_mov_b32_e32 v24, v194
	v_mov_b32_e32 v25, v194
	v_mov_b32_e32 v26, v194
	v_mov_b32_e32 v27, v194
	v_mov_b32_e32 v28, v194
	v_mov_b32_e32 v29, v194
	v_mov_b32_e32 v30, v194
	v_mov_b32_e32 v31, v194
	v_mov_b32_e32 v32, v194
	v_mov_b32_e32 v33, v194
	v_mov_b32_e32 v2, v194
	v_mov_b32_e32 v3, v194
	v_mov_b32_e32 v4, v194
	v_mov_b32_e32 v5, v194
	v_mov_b32_e32 v6, v194
	v_mov_b32_e32 v7, v194
	v_mov_b32_e32 v8, v194
	v_mov_b32_e32 v9, v194
	v_mov_b32_e32 v10, v194
	v_mov_b32_e32 v11, v194
	v_mov_b32_e32 v12, v194
	v_mov_b32_e32 v13, v194
	v_mov_b32_e32 v14, v194
	v_mov_b32_e32 v15, v194
	v_mov_b32_e32 v16, v194
	v_mov_b32_e32 v17, v194
	v_readfirstlane_b32 s98, v186
	v_readfirstlane_b32 s99, v187
	v_readfirstlane_b32 s100, v184
	v_readfirstlane_b32 s101, v185
	s_nop 1
	v_subrev_u32_e32 v226, s98, v186
	v_subrev_u32_e32 v228, s100, v184
	v_add_u32_e32 v227, 0x4000, v226
	v_add_u32_e32 v229, 0x4000, v228
	s_nop 1
	s_add_u32 s98, s98, s12
	s_addc_u32 s99, s99, s13
	s_add_u32 s98, s98, s0
	s_addc_u32 s99, s99, s1
	s_add_u32 s100, s100, s12
	s_addc_u32 s101, s101, s13
	s_add_u32 s100, s100, s66
	s_addc_u32 s101, s101, s67
.LBB0_381:
	v_add_u32_e32 v183, s20, v209
	ds_read_b64_tr_b16 v[178:179], v183 offset:24576
	ds_read_b64_tr_b16 v[180:181], v183 offset:25088
	s_waitcnt lgkmcnt(9)
	v_mfma_f32_32x32x16_bf16 v[98:113], v[174:177], v[142:145], v[34:49]
	v_add_f32_e32 v82, v66, v67
	v_add_f32_e32 v82, v68, v82
	v_add_f32_e32 v82, v69, v82
	v_add_f32_e32 v82, v70, v82
	v_add_f32_e32 v82, v71, v82
	v_cvt_pk_bf16_f32 v138, v66, v67
	v_cvt_pk_bf16_f32 v139, v68, v69
	ds_read_b64_tr_b16 v[174:175], v183 offset:28672
	ds_read_b64_tr_b16 v[176:177], v183 offset:29184
	v_add_f32_e32 v66, v72, v82
	s_waitcnt lgkmcnt(10)
	v_mfma_f32_32x32x16_bf16 v[82:97], v[170:173], v[142:145], v[34:49]
	v_add_f32_e32 v66, v73, v66
	v_add_f32_e32 v66, v74, v66
	v_add_f32_e32 v114, v75, v66
	v_cvt_pk_bf16_f32 v140, v70, v71
	v_cvt_pk_bf16_f32 v141, v72, v73
	ds_read_b64_tr_b16 v[66:67], v183 offset:25600
	ds_read_b64_tr_b16 v[68:69], v183 offset:26112
	s_waitcnt lgkmcnt(11)
	v_mfma_f32_32x32x16_bf16 v[98:113], v[166:169], v[134:137], v[98:113]
	v_add_f32_e32 v70, v76, v114
	v_add_f32_e32 v70, v77, v70
	v_add_f32_e32 v70, v78, v70
	v_add_f32_e32 v114, v79, v70
	v_cvt_pk_bf16_f32 v130, v74, v75
	v_cvt_pk_bf16_f32 v131, v76, v77
	ds_read_b64_tr_b16 v[70:71], v183 offset:29696
	ds_read_b64_tr_b16 v[72:73], v183 offset:30208
	s_waitcnt lgkmcnt(12)
	v_mfma_f32_32x32x16_bf16 v[82:97], v[162:165], v[134:137], v[82:97]
	v_add_f32_e32 v74, v80, v114
	v_add_f32_e32 v74, v81, v74
	v_add_f32_e32 v74, v50, v74
	v_add_f32_e32 v114, v51, v74
	v_cvt_pk_bf16_f32 v132, v78, v79
	v_cvt_pk_bf16_f32 v133, v80, v81
	ds_read_b64_tr_b16 v[74:75], v183 offset:26624
	ds_read_b64_tr_b16 v[76:77], v183 offset:27136
	s_waitcnt lgkmcnt(13)
	v_mfma_f32_32x32x16_bf16 v[98:113], v[158:161], v[126:129], v[98:113]
	v_add_f32_e32 v78, v52, v114
	v_add_f32_e32 v78, v53, v78
	v_add_f32_e32 v78, v54, v78
	v_add_f32_e32 v78, v55, v78
	v_cvt_pk_bf16_f32 v122, v50, v51
	v_cvt_pk_bf16_f32 v123, v52, v53
	ds_read_b64_tr_b16 v[50:51], v183 offset:30720
	ds_read_b64_tr_b16 v[52:53], v183 offset:31232
	s_waitcnt lgkmcnt(14)
	v_mfma_f32_32x32x16_bf16 v[82:97], v[154:157], v[126:129], v[82:97]
	v_add_f32_e32 v78, v56, v78
	v_add_f32_e32 v78, v57, v78
	v_add_f32_e32 v78, v58, v78
	v_add_f32_e32 v78, v59, v78
	v_cvt_pk_bf16_f32 v124, v54, v55
	v_cvt_pk_bf16_f32 v125, v56, v57
	ds_read_b64_tr_b16 v[54:55], v183 offset:27648
	ds_read_b64_tr_b16 v[56:57], v183 offset:28160
	s_waitcnt lgkmcnt(14)
	v_mfma_f32_32x32x16_bf16 v[98:113], v[150:153], v[118:121], v[98:113]
	v_add_f32_e32 v78, v60, v78
	v_add_f32_e32 v78, v61, v78
	v_add_f32_e32 v78, v62, v78
	v_add_f32_e32 v78, v63, v78
	v_cvt_pk_bf16_f32 v114, v58, v59
	v_cvt_pk_bf16_f32 v115, v60, v61
	ds_read_b64_tr_b16 v[58:59], v183 offset:31744
	ds_read_b64_tr_b16 v[60:61], v183 offset:32256
	v_mfma_f32_32x32x16_bf16 v[82:97], v[146:149], v[118:121], v[82:97]
	v_add_f32_e32 v78, v64, v78
	v_add_f32_e32 v78, v65, v78
	v_cvt_pk_bf16_f32 v116, v62, v63
	v_cvt_pk_bf16_f32 v117, v64, v65
	s_add_i32 s20, s72, s29
	s_mov_b32 s21, m0
	s_mov_b32 m0, s20
	s_nop 0
	global_load_lds_dwordx4 v226, s[98:99]
	s_mov_b32 m0, s21
	s_add_i32 s20, s36, s30
	s_mov_b32 s21, m0
	s_mov_b32 m0, s20
	s_nop 0
	global_load_lds_dwordx4 v228, s[100:101]
	s_mov_b32 m0, s21
	v_max_f32_e32 v62, v98, v99
	v_max3_f32 v63, v100, v101, v83
	v_max3_f32 v62, v62, v82, v84
	v_max3_f32 v62, v62, v85, v102
	v_max3_f32 v63, v63, v104, v105
	v_max3_f32 v62, v62, v103, v86
	v_max3_f32 v63, v63, v88, v89
	v_max3_f32 v62, v62, v87, v106
	v_max3_f32 v63, v63, v108, v109
	v_max3_f32 v62, v62, v107, v90
	v_max3_f32 v63, v63, v92, v93
	v_max3_f32 v62, v62, v91, v110
	v_max3_f32 v63, v63, v112, v113
	v_max3_f32 v62, v62, v111, v94
	v_max3_f32 v63, v63, v96, v97
	v_max3_f32 v62, v62, v95, v63
	v_mov_b32_e32 v63, v62
	s_nop 1
	v_permlane32_swap_b32_e32 v62, v63
	v_max_f32_e32 v62, v62, v63
	v_cmp_lt_f32_e32 vcc, s69, v62
	s_cmp_lg_u64 vcc, 0
	v_add_f32_e32 v183, v194, v78
	s_cselect_b64 s[20:21], -1, 0
	s_cbranch_vccnz .LBB0_389

.LBB0_384:
	s_add_i32 s20, s36, 0x2000
	s_cmpk_lg_i32 s36, 0x4000
	s_cselect_b32 s35, s20, 0
	v_add_u32_e32 v194, s72, v209
	ds_read_b64_tr_b16 v[150:151], v194 offset:24576
	ds_read_b64_tr_b16 v[152:153], v194 offset:25088
	s_waitcnt lgkmcnt(9)
	v_mfma_f32_32x32x16_bf16 v[66:81], v[62:65], v[142:145], v[34:49]
	v_add_f32_e32 v50, v98, v99
	v_add_f32_e32 v50, v100, v50
	v_add_f32_e32 v50, v101, v50
	v_add_f32_e32 v50, v102, v50
	v_add_f32_e32 v50, v103, v50
	v_cvt_pk_bf16_f32 v138, v98, v99
	v_cvt_pk_bf16_f32 v139, v100, v101
	ds_read_b64_tr_b16 v[146:147], v194 offset:28672
	ds_read_b64_tr_b16 v[148:149], v194 offset:29184
	v_add_f32_e32 v50, v104, v50
	v_add_f32_e32 v50, v105, v50
	v_add_f32_e32 v50, v106, v50
	v_add_f32_e32 v114, v107, v50
	s_waitcnt lgkmcnt(10)
	v_mfma_f32_32x32x16_bf16 v[50:65], v[174:177], v[142:145], v[34:49]
	v_cvt_pk_bf16_f32 v140, v102, v103
	v_cvt_pk_bf16_f32 v141, v104, v105
	ds_read_b64_tr_b16 v[98:99], v194 offset:25600
	ds_read_b64_tr_b16 v[100:101], v194 offset:26112
	s_waitcnt lgkmcnt(11)
	v_mfma_f32_32x32x16_bf16 v[66:81], v[178:181], v[134:137], v[66:81]
	v_add_f32_e32 v102, v108, v114
	v_add_f32_e32 v102, v109, v102
	v_add_f32_e32 v102, v110, v102
	v_add_f32_e32 v114, v111, v102
	v_cvt_pk_bf16_f32 v130, v106, v107
	v_cvt_pk_bf16_f32 v131, v108, v109
	ds_read_b64_tr_b16 v[102:103], v194 offset:29696
	ds_read_b64_tr_b16 v[104:105], v194 offset:30208
	s_waitcnt lgkmcnt(12)
	v_mfma_f32_32x32x16_bf16 v[50:65], v[170:173], v[134:137], v[50:65]
	v_add_f32_e32 v106, v112, v114
	v_add_f32_e32 v106, v113, v106
	v_add_f32_e32 v106, v82, v106
	v_add_f32_e32 v114, v83, v106
	v_cvt_pk_bf16_f32 v132, v110, v111
	v_cvt_pk_bf16_f32 v133, v112, v113
	ds_read_b64_tr_b16 v[106:107], v194 offset:26624
	ds_read_b64_tr_b16 v[108:109], v194 offset:27136
	s_waitcnt lgkmcnt(13)
	v_mfma_f32_32x32x16_bf16 v[66:81], v[166:169], v[126:129], v[66:81]
	v_add_f32_e32 v110, v84, v114
	v_add_f32_e32 v110, v85, v110
	v_add_f32_e32 v110, v86, v110
	v_add_f32_e32 v110, v87, v110
	v_cvt_pk_bf16_f32 v122, v82, v83
	v_cvt_pk_bf16_f32 v123, v84, v85
	ds_read_b64_tr_b16 v[82:83], v194 offset:30720
	ds_read_b64_tr_b16 v[84:85], v194 offset:31232
	s_waitcnt lgkmcnt(14)
	v_mfma_f32_32x32x16_bf16 v[50:65], v[162:165], v[126:129], v[50:65]
	v_add_f32_e32 v110, v88, v110
	v_add_f32_e32 v110, v89, v110
	v_add_f32_e32 v110, v90, v110
	v_add_f32_e32 v110, v91, v110
	v_cvt_pk_bf16_f32 v124, v86, v87
	v_cvt_pk_bf16_f32 v125, v88, v89
	ds_read_b64_tr_b16 v[86:87], v194 offset:27648
	ds_read_b64_tr_b16 v[88:89], v194 offset:28160
	s_waitcnt lgkmcnt(14)
	v_mfma_f32_32x32x16_bf16 v[66:81], v[158:161], v[118:121], v[66:81]
	v_add_f32_e32 v110, v92, v110
	v_add_f32_e32 v110, v93, v110
	v_add_f32_e32 v110, v94, v110
	v_add_f32_e32 v110, v95, v110
	v_cvt_pk_bf16_f32 v114, v90, v91
	v_cvt_pk_bf16_f32 v115, v92, v93
	ds_read_b64_tr_b16 v[90:91], v194 offset:31744
	ds_read_b64_tr_b16 v[92:93], v194 offset:32256
	v_mfma_f32_32x32x16_bf16 v[50:65], v[154:157], v[118:121], v[50:65]
	v_add_f32_e32 v110, v96, v110
	v_add_f32_e32 v110, v97, v110
	v_cvt_pk_bf16_f32 v116, v94, v95
	v_cvt_pk_bf16_f32 v117, v96, v97
	s_add_i32 s20, s36, s29
	s_mov_b32 s21, m0
	s_mov_b32 m0, s20
	s_nop 0
	global_load_lds_dwordx4 v227, s[98:99]
	s_mov_b32 m0, s21
	s_add_i32 s20, s35, s30
	s_mov_b32 s21, m0
	s_mov_b32 m0, s20
	s_nop 0
	global_load_lds_dwordx4 v229, s[100:101]
	s_mov_b32 m0, s21
	v_max_f32_e32 v94, v66, v67
	v_max3_f32 v95, v68, v69, v51
	v_max3_f32 v94, v94, v50, v52
	v_max3_f32 v94, v94, v53, v70
	v_max3_f32 v95, v95, v72, v73
	v_max3_f32 v94, v94, v71, v54
	v_max3_f32 v95, v95, v56, v57
	v_max3_f32 v94, v94, v55, v74
	v_max3_f32 v95, v95, v76, v77
	v_max3_f32 v94, v94, v75, v58
	v_max3_f32 v95, v95, v60, v61
	v_max3_f32 v94, v94, v59, v78
	v_max3_f32 v95, v95, v80, v81
	v_max3_f32 v94, v94, v79, v62
	v_max3_f32 v95, v95, v64, v65
	v_max3_f32 v94, v94, v63, v95
	v_mov_b32_e32 v95, v94
	s_nop 1
	v_permlane32_swap_b32_e32 v94, v95
	v_max_f32_e32 v94, v94, v95
	v_cmp_lt_f32_e32 vcc, s69, v94
	s_cmp_lg_u64 vcc, 0
	v_add_f32_e32 v194, v183, v110
	s_cselect_b64 s[20:21], -1, 0
	s_cbranch_vccnz .LBB0_392

.LBB0_387:
	s_add_u32 s98, s98, s62
	s_addc_u32 s99, s99, s63
	s_add_u32 s100, s100, s62
	s_addc_u32 s101, s101, s63
	s_add_i32 s20, s35, 0x2000
	s_cmpk_lg_i32 s35, 0x4000
	s_cselect_b32 s37, s20, 0
	s_add_i32 s20, s41, 2
	s_cmp_ge_u32 s20, s28
	s_cbranch_scc1 .LBB0_402
	s_mov_b32 s41, s20
	s_mov_b32 s20, s36
	s_mov_b32 s72, s35
	s_mov_b32 s36, s37
	s_branch .LBB0_381

	.amdhsa_kernel _Z10hybrid_fwd6Params
		.amdhsa_group_segment_fixed_size 0
		.amdhsa_private_segment_fixed_size 0
		.amdhsa_kernarg_size 440
		.amdhsa_user_sgpr_count 2
		.amdhsa_user_sgpr_dispatch_ptr 0
		.amdhsa_user_sgpr_queue_ptr 0
		.amdhsa_user_sgpr_kernarg_segment_ptr 1
		.amdhsa_user_sgpr_dispatch_id 0
		.amdhsa_user_sgpr_kernarg_preload_length 0
		.amdhsa_user_sgpr_kernarg_preload_offset 0
		.amdhsa_user_sgpr_private_segment_size 0
		.amdhsa_uses_dynamic_stack 0
		.amdhsa_enable_private_segment 0
		.amdhsa_system_sgpr_workgroup_id_x 1
		.amdhsa_system_sgpr_workgroup_id_y 0
		.amdhsa_system_sgpr_workgroup_id_z 0
		.amdhsa_system_sgpr_workgroup_info 0
		.amdhsa_system_vgpr_workitem_id 2
		.amdhsa_next_free_vgpr 256
		.amdhsa_next_free_sgpr 102
		.amdhsa_accum_offset 256
		.amdhsa_reserve_vcc 1
		.amdhsa_float_round_mode_32 0
		.amdhsa_float_round_mode_16_64 0
		.amdhsa_float_denorm_mode_32 3
		.amdhsa_float_denorm_mode_16_64 3
		.amdhsa_dx10_clamp 1
		.amdhsa_ieee_mode 1
		.amdhsa_fp16_overflow 0
		.amdhsa_tg_split 0
		.amdhsa_exception_fp_ieee_invalid_op 0
		.amdhsa_exception_fp_denorm_src 0
		.amdhsa_exception_fp_ieee_div_zero 0
		.amdhsa_exception_fp_ieee_overflow 0
		.amdhsa_exception_fp_ieee_underflow 0
		.amdhsa_exception_fp_ieee_inexact 0
		.amdhsa_exception_int_div_zero 0
	.end_amdhsa_kernel

amdhsa.kernels:
  - .agpr_count:     0
    .args:
      - .offset:         0
        .size:           184
        .value_kind:     by_value
      - .offset:         184
        .size:           4
        .value_kind:     hidden_block_count_x
      - .offset:         188
        .size:           4
        .value_kind:     hidden_block_count_y
      - .offset:         192
        .size:           4
        .value_kind:     hidden_block_count_z
      - .offset:         196
        .size:           2
        .value_kind:     hidden_group_size_x
      - .offset:         198
        .size:           2
        .value_kind:     hidden_group_size_y
      - .offset:         200
        .size:           2
        .value_kind:     hidden_group_size_z
      - .offset:         202
        .size:           2
        .value_kind:     hidden_remainder_x
      - .offset:         204
        .size:           2
        .value_kind:     hidden_remainder_y
      - .offset:         206
        .size:           2
        .value_kind:     hidden_remainder_z
      - .offset:         224
        .size:           8
        .value_kind:     hidden_global_offset_x
      - .offset:         232
        .size:           8
        .value_kind:     hidden_global_offset_y
      - .offset:         240
        .size:           8
        .value_kind:     hidden_global_offset_z
      - .offset:         248
        .size:           2
        .value_kind:     hidden_grid_dims
      - .offset:         272
        .size:           8
        .value_kind:     hidden_multigrid_sync_arg
      - .offset:         304
        .size:           4
        .value_kind:     hidden_dynamic_lds_size
    .group_segment_fixed_size: 0
    .kernarg_segment_align: 8
    .kernarg_segment_size: 440
    .language:       OpenCL C
    .language_version:
      - 2
      - 0
    .max_flat_workgroup_size: 512
    .name:           _Z10hybrid_fwd6Params
    .private_segment_fixed_size: 0
    .sgpr_count:     108
    .sgpr_spill_count: 213
    .symbol:         _Z10hybrid_fwd6Params.kd
    .uniform_work_group_size: 1
    .uses_dynamic_stack: false
    .vgpr_count:     256
    .vgpr_spill_count: 0
    .wavefront_size: 64
